# flattened grid barrier, per-XCD arrival counters each on their own 256B-strided line
# baseline (speedup 1.0000x reference)
; DEV unsigned xb_ld(unsigned* p) { return __hip_atomic_load(p, __ATOMIC_RELAXED, __HIP_MEMORY_SCOPE_AGENT); }
; DEV unsigned xb_add(unsigned* p, unsigned v) { return __hip_atomic_fetch_add(p, v, __ATOMIC_RELAXED, __HIP_MEMORY_SCOPE_AGENT); }
; #define XB_SPIN(cond, bar) do { unsigned _sp = 0; while (cond) { __builtin_amdgcn_s_sleep(1); \
;     if ((++_sp & 255u) == 0u) { if (xb_ld(&(bar)[XB_TMO])) break; if (_sp > XB_SPIN_CAP) { atomicAdd(&(bar)[XB_TMO], 1u); break; } } } } while (0)
; DEV void xcd_barrier(const XcdBarrier& b) {
;   asm volatile("s_waitcnt vmcnt(0)" ::: "memory");
;   __syncthreads();
;   if (threadIdx.x == 0) {
;     unsigned* bar = b.bar;
;     __builtin_amdgcn_s_waitcnt(0);
;     unsigned nloc = b.st[0], nx = b.st[1];
;     if (nloc == 0u) { xcd_barrier_complete(bar, b.x, nloc, nx); b.st[0] = nloc; b.st[1] = nx; }
;     const unsigned old = xb_add(&bar[XB_XSUB(b.x)], 1u);
;     const unsigned gen = old / nloc;
;     if (old + 1u == (gen + 1u) * nloc) {
;       __builtin_amdgcn_fence(__ATOMIC_RELEASE, "agent");
;       asm volatile("s_waitcnt vmcnt(0)" ::: "memory");
;       const unsigned og = xb_add(&bar[XB_TOP], 1u);
;       const unsigned tg = og / nx;
;       if (og + 1u == (tg + 1u) * nx) xb_add(&bar[XB_TOPGEN], 1u);
;       else XB_SPIN(xb_ld(&bar[XB_TOPGEN]) == tg, bar);
;       __builtin_amdgcn_fence(__ATOMIC_ACQUIRE, "agent");
;       xb_add(&bar[XB_XGEN(b.x)], 1u);
;       asm volatile("s_waitcnt vmcnt(0)" ::: "memory");
;     } else {
;       XB_SPIN(xb_ld(&bar[XB_XGEN(b.x)]) == gen, bar);
;       __builtin_amdgcn_fence(__ATOMIC_ACQUIRE, "agent");
;       asm volatile("s_waitcnt vmcnt(0)" ::: "memory");
;     }
;   }
;   __syncthreads();
; }
.LBB0_203:
	s_waitcnt vmcnt(0)
	s_waitcnt lgkmcnt(0)
	s_barrier
	s_mov_b64 s[0:1], exec
	v_readlane_b32 s14, v251, 1
	v_readlane_b32 s15, v251, 2
	s_and_b64 s[14:15], s[0:1], s[14:15]
	s_mov_b64 exec, s[14:15]
	s_cbranch_execz .LBB0_251
	s_waitcnt vmcnt(0) expcnt(0) lgkmcnt(0)
	ds_read_b32 v2, v193
	ds_read_b32 v0, v194
	global_atomic_add v3, v[176:177], v195, off sc0
	v_readlane_b32 s16, v251, 3
	v_readlane_b32 s17, v251, 4
	s_waitcnt lgkmcnt(0)
	v_cvt_f32_u32_e32 v1, v2
	v_sub_u32_e32 v4, 0, v2
	v_rcp_iflag_f32_e32 v1, v1
	s_add_u32 s16, s16, 0x2480
	s_addc_u32 s17, s17, 0
	v_mul_f32_e32 v1, 0x4f7ffffe, v1
	v_cvt_u32_f32_e32 v1, v1
	v_mul_lo_u32 v4, v4, v1
	v_mul_hi_u32 v4, v1, v4
	v_add_u32_e32 v1, v1, v4
	s_waitcnt vmcnt(0)
	v_mul_hi_u32 v1, v3, v1
	v_mul_lo_u32 v4, v1, v2
	v_sub_u32_e32 v4, v3, v4
	v_add_u32_e32 v5, 1, v1
	v_cmp_ge_u32_e32 vcc, v4, v2
	v_add_u32_e32 v3, 1, v3
	s_nop 1
	v_cndmask_b32_e32 v1, v1, v5, vcc
	v_sub_u32_e32 v5, v4, v2
	v_cndmask_b32_e32 v4, v4, v5, vcc
	v_add_u32_e32 v5, 1, v1
	v_cmp_ge_u32_e32 vcc, v4, v2
	s_nop 1
	v_cndmask_b32_e32 v1, v1, v5, vcc
	v_mul_lo_u32 v4, v2, v1
	v_add_u32_e32 v2, v4, v2
	v_mul_lo_u32 v5, v1, v0
	v_cmp_eq_u32_e32 vcc, v3, v2
	s_and_saveexec_b64 s[14:15], vcc
	s_cbranch_execz Lxb1_poll
	buffer_wbl2 sc1
	s_waitcnt vmcnt(0)
	global_atomic_add v181, v195, s[16:17]
	global_atomic_add v181, v195, s[16:17] offset:256
	global_atomic_add v181, v195, s[16:17] offset:512
	global_atomic_add v181, v195, s[16:17] offset:768
	global_atomic_add v181, v195, s[16:17] offset:1024
	global_atomic_add v181, v195, s[16:17] offset:1280
	global_atomic_add v181, v195, s[16:17] offset:1536
	global_atomic_add v181, v195, s[16:17] offset:1792
	global_atomic_add v181, v195, s[16:17] offset:2048
	global_atomic_add v181, v195, s[16:17] offset:2304
	global_atomic_add v181, v195, s[16:17] offset:2560
	global_atomic_add v181, v195, s[16:17] offset:2816
	global_atomic_add v181, v195, s[16:17] offset:3072
	global_atomic_add v181, v195, s[16:17] offset:3328
	global_atomic_add v181, v195, s[16:17] offset:3584
	global_atomic_add v181, v195, s[16:17] offset:3840
Lxb1_poll:
	s_or_b64 exec, exec, s[14:15]
	v_subrev_u32_e32 v4, s16, v176
	v_add_u32_e32 v4, 0x1080, v4
	s_mov_b32 s6, 0

; DEV unsigned xb_ld(unsigned* p) { return __hip_atomic_load(p, __ATOMIC_RELAXED, __HIP_MEMORY_SCOPE_AGENT); }
; DEV unsigned xb_add(unsigned* p, unsigned v) { return __hip_atomic_fetch_add(p, v, __ATOMIC_RELAXED, __HIP_MEMORY_SCOPE_AGENT); }
; #define XB_SPIN(cond, bar) do { unsigned _sp = 0; while (cond) { __builtin_amdgcn_s_sleep(1); \
;     if ((++_sp & 255u) == 0u) { if (xb_ld(&(bar)[XB_TMO])) break; if (_sp > XB_SPIN_CAP) { atomicAdd(&(bar)[XB_TMO], 1u); break; } } } } while (0)
; DEV void xcd_barrier(const XcdBarrier& b) {
;   asm volatile("s_waitcnt vmcnt(0)" ::: "memory");
;   __syncthreads();
;   if (threadIdx.x == 0) {
;     unsigned* bar = b.bar;
;     __builtin_amdgcn_s_waitcnt(0);
;     unsigned nloc = b.st[0], nx = b.st[1];
;     if (nloc == 0u) { xcd_barrier_complete(bar, b.x, nloc, nx); b.st[0] = nloc; b.st[1] = nx; }
;     const unsigned old = xb_add(&bar[XB_XSUB(b.x)], 1u);
;     const unsigned gen = old / nloc;
;     if (old + 1u == (gen + 1u) * nloc) {
;       __builtin_amdgcn_fence(__ATOMIC_RELEASE, "agent");
;       asm volatile("s_waitcnt vmcnt(0)" ::: "memory");
;       const unsigned og = xb_add(&bar[XB_TOP], 1u);
;       const unsigned tg = og / nx;
;       if (og + 1u == (tg + 1u) * nx) xb_add(&bar[XB_TOPGEN], 1u);
;       else XB_SPIN(xb_ld(&bar[XB_TOPGEN]) == tg, bar);
;       __builtin_amdgcn_fence(__ATOMIC_ACQUIRE, "agent");
;       xb_add(&bar[XB_XGEN(b.x)], 1u);
;       asm volatile("s_waitcnt vmcnt(0)" ::: "memory");
;     } else {
;       XB_SPIN(xb_ld(&bar[XB_XGEN(b.x)]) == gen, bar);
;       __builtin_amdgcn_fence(__ATOMIC_ACQUIRE, "agent");
;       asm volatile("s_waitcnt vmcnt(0)" ::: "memory");
;     }
;   }
;   __syncthreads();
; }
.LBB0_276:
	s_or_b64 exec, exec, s[0:1]
	s_waitcnt vmcnt(0)
	s_waitcnt lgkmcnt(0)
	s_barrier
	s_mov_b64 s[0:1], exec
	v_readlane_b32 s4, v251, 1
	v_readlane_b32 s5, v251, 2
	s_and_b64 s[4:5], s[0:1], s[4:5]
	s_movk_i32 s31, 0x70
	s_mov_b64 exec, s[4:5]
	s_cbranch_execz .LBB0_325
	s_waitcnt vmcnt(0) expcnt(0) lgkmcnt(0)
	ds_read_b32 v2, v193
	ds_read_b32 v0, v194
	global_atomic_add v3, v[176:177], v195, off sc0
	v_readlane_b32 s14, v251, 3
	v_readlane_b32 s15, v251, 4
	s_waitcnt lgkmcnt(0)
	v_cvt_f32_u32_e32 v1, v2
	v_sub_u32_e32 v4, 0, v2
	v_rcp_iflag_f32_e32 v1, v1
	s_add_u32 s14, s14, 0x2480
	s_addc_u32 s15, s15, 0
	v_mul_f32_e32 v1, 0x4f7ffffe, v1
	v_cvt_u32_f32_e32 v1, v1
	v_mul_lo_u32 v4, v4, v1
	v_mul_hi_u32 v4, v1, v4
	v_add_u32_e32 v1, v1, v4
	s_waitcnt vmcnt(0)
	v_mul_hi_u32 v1, v3, v1
	v_mul_lo_u32 v4, v1, v2
	v_sub_u32_e32 v4, v3, v4
	v_add_u32_e32 v5, 1, v1
	v_cmp_ge_u32_e32 vcc, v4, v2
	v_add_u32_e32 v3, 1, v3
	s_nop 1
	v_cndmask_b32_e32 v1, v1, v5, vcc
	v_sub_u32_e32 v5, v4, v2
	v_cndmask_b32_e32 v4, v4, v5, vcc
	v_add_u32_e32 v5, 1, v1
	v_cmp_ge_u32_e32 vcc, v4, v2
	s_nop 1
	v_cndmask_b32_e32 v1, v1, v5, vcc
	v_mul_lo_u32 v4, v2, v1
	v_add_u32_e32 v2, v4, v2
	v_mul_lo_u32 v5, v1, v0
	v_cmp_eq_u32_e32 vcc, v3, v2
	s_and_saveexec_b64 s[4:5], vcc
	s_cbranch_execz Lxb2_poll
	buffer_wbl2 sc1
	s_waitcnt vmcnt(0)
	global_atomic_add v181, v195, s[14:15]
	global_atomic_add v181, v195, s[14:15] offset:256
	global_atomic_add v181, v195, s[14:15] offset:512
	global_atomic_add v181, v195, s[14:15] offset:768
	global_atomic_add v181, v195, s[14:15] offset:1024
	global_atomic_add v181, v195, s[14:15] offset:1280
	global_atomic_add v181, v195, s[14:15] offset:1536
	global_atomic_add v181, v195, s[14:15] offset:1792
	global_atomic_add v181, v195, s[14:15] offset:2048
	global_atomic_add v181, v195, s[14:15] offset:2304
	global_atomic_add v181, v195, s[14:15] offset:2560
	global_atomic_add v181, v195, s[14:15] offset:2816
	global_atomic_add v181, v195, s[14:15] offset:3072
	global_atomic_add v181, v195, s[14:15] offset:3328
	global_atomic_add v181, v195, s[14:15] offset:3584
	global_atomic_add v181, v195, s[14:15] offset:3840
Lxb2_poll:
	s_or_b64 exec, exec, s[4:5]
	v_subrev_u32_e32 v4, s14, v176
	v_add_u32_e32 v4, 0x1080, v4
	s_mov_b32 s6, 0

; DEV unsigned xb_ld(unsigned* p) { return __hip_atomic_load(p, __ATOMIC_RELAXED, __HIP_MEMORY_SCOPE_AGENT); }
; DEV unsigned xb_add(unsigned* p, unsigned v) { return __hip_atomic_fetch_add(p, v, __ATOMIC_RELAXED, __HIP_MEMORY_SCOPE_AGENT); }
; #define XB_SPIN(cond, bar) do { unsigned _sp = 0; while (cond) { __builtin_amdgcn_s_sleep(1); \
;     if ((++_sp & 255u) == 0u) { if (xb_ld(&(bar)[XB_TMO])) break; if (_sp > XB_SPIN_CAP) { atomicAdd(&(bar)[XB_TMO], 1u); break; } } } } while (0)
; DEV void xcd_barrier(const XcdBarrier& b) {
;   asm volatile("s_waitcnt vmcnt(0)" ::: "memory");
;   __syncthreads();
;   if (threadIdx.x == 0) {
;     unsigned* bar = b.bar;
;     __builtin_amdgcn_s_waitcnt(0);
;     unsigned nloc = b.st[0], nx = b.st[1];
;     if (nloc == 0u) { xcd_barrier_complete(bar, b.x, nloc, nx); b.st[0] = nloc; b.st[1] = nx; }
;     const unsigned old = xb_add(&bar[XB_XSUB(b.x)], 1u);
;     const unsigned gen = old / nloc;
;     if (old + 1u == (gen + 1u) * nloc) {
;       __builtin_amdgcn_fence(__ATOMIC_RELEASE, "agent");
;       asm volatile("s_waitcnt vmcnt(0)" ::: "memory");
;       const unsigned og = xb_add(&bar[XB_TOP], 1u);
;       const unsigned tg = og / nx;
;       if (og + 1u == (tg + 1u) * nx) xb_add(&bar[XB_TOPGEN], 1u);
;       else XB_SPIN(xb_ld(&bar[XB_TOPGEN]) == tg, bar);
;       __builtin_amdgcn_fence(__ATOMIC_ACQUIRE, "agent");
;       xb_add(&bar[XB_XGEN(b.x)], 1u);
;       asm volatile("s_waitcnt vmcnt(0)" ::: "memory");
;     } else {
;       XB_SPIN(xb_ld(&bar[XB_XGEN(b.x)]) == gen, bar);
;       __builtin_amdgcn_fence(__ATOMIC_ACQUIRE, "agent");
;       asm volatile("s_waitcnt vmcnt(0)" ::: "memory");
;     }
;   }
;   __syncthreads();
; }
.LBB0_349:
	s_waitcnt vmcnt(0)
	s_waitcnt lgkmcnt(0)
	s_barrier
	s_mov_b64 s[0:1], exec
	v_readlane_b32 s4, v251, 1
	v_readlane_b32 s5, v251, 2
	s_and_b64 s[4:5], s[0:1], s[4:5]
	s_mov_b64 exec, s[4:5]
	s_cbranch_execz .LBB0_397
	s_waitcnt vmcnt(0) expcnt(0) lgkmcnt(0)
	ds_read_b32 v2, v193
	ds_read_b32 v0, v194
	global_atomic_add v3, v[176:177], v195, off sc0
	v_readlane_b32 s14, v251, 3
	v_readlane_b32 s15, v251, 4
	s_waitcnt lgkmcnt(0)
	v_cvt_f32_u32_e32 v1, v2
	v_sub_u32_e32 v4, 0, v2
	v_rcp_iflag_f32_e32 v1, v1
	s_add_u32 s14, s14, 0x2480
	s_addc_u32 s15, s15, 0
	v_mul_f32_e32 v1, 0x4f7ffffe, v1
	v_cvt_u32_f32_e32 v1, v1
	v_mul_lo_u32 v4, v4, v1
	v_mul_hi_u32 v4, v1, v4
	v_add_u32_e32 v1, v1, v4
	s_waitcnt vmcnt(0)
	v_mul_hi_u32 v1, v3, v1
	v_mul_lo_u32 v4, v1, v2
	v_sub_u32_e32 v4, v3, v4
	v_add_u32_e32 v5, 1, v1
	v_cmp_ge_u32_e32 vcc, v4, v2
	v_add_u32_e32 v3, 1, v3
	s_nop 1
	v_cndmask_b32_e32 v1, v1, v5, vcc
	v_sub_u32_e32 v5, v4, v2
	v_cndmask_b32_e32 v4, v4, v5, vcc
	v_add_u32_e32 v5, 1, v1
	v_cmp_ge_u32_e32 vcc, v4, v2
	s_nop 1
	v_cndmask_b32_e32 v1, v1, v5, vcc
	v_mul_lo_u32 v4, v2, v1
	v_add_u32_e32 v2, v4, v2
	v_mul_lo_u32 v5, v1, v0
	v_cmp_eq_u32_e32 vcc, v3, v2
	s_and_saveexec_b64 s[4:5], vcc
	s_cbranch_execz Lxb3_poll
	buffer_wbl2 sc1
	s_waitcnt vmcnt(0)
	global_atomic_add v181, v195, s[14:15]
	global_atomic_add v181, v195, s[14:15] offset:256
	global_atomic_add v181, v195, s[14:15] offset:512
	global_atomic_add v181, v195, s[14:15] offset:768
	global_atomic_add v181, v195, s[14:15] offset:1024
	global_atomic_add v181, v195, s[14:15] offset:1280
	global_atomic_add v181, v195, s[14:15] offset:1536
	global_atomic_add v181, v195, s[14:15] offset:1792
	global_atomic_add v181, v195, s[14:15] offset:2048
	global_atomic_add v181, v195, s[14:15] offset:2304
	global_atomic_add v181, v195, s[14:15] offset:2560
	global_atomic_add v181, v195, s[14:15] offset:2816
	global_atomic_add v181, v195, s[14:15] offset:3072
	global_atomic_add v181, v195, s[14:15] offset:3328
	global_atomic_add v181, v195, s[14:15] offset:3584
	global_atomic_add v181, v195, s[14:15] offset:3840
Lxb3_poll:
	s_or_b64 exec, exec, s[4:5]
	v_subrev_u32_e32 v4, s14, v176
	v_add_u32_e32 v4, 0x1080, v4
	s_mov_b32 s6, 0

; DEV unsigned xb_ld(unsigned* p) { return __hip_atomic_load(p, __ATOMIC_RELAXED, __HIP_MEMORY_SCOPE_AGENT); }
; DEV unsigned xb_add(unsigned* p, unsigned v) { return __hip_atomic_fetch_add(p, v, __ATOMIC_RELAXED, __HIP_MEMORY_SCOPE_AGENT); }
; #define XB_SPIN(cond, bar) do { unsigned _sp = 0; while (cond) { __builtin_amdgcn_s_sleep(1); \
;     if ((++_sp & 255u) == 0u) { if (xb_ld(&(bar)[XB_TMO])) break; if (_sp > XB_SPIN_CAP) { atomicAdd(&(bar)[XB_TMO], 1u); break; } } } } while (0)
; DEV void xcd_barrier(const XcdBarrier& b) {
;   asm volatile("s_waitcnt vmcnt(0)" ::: "memory");
;   __syncthreads();
;   if (threadIdx.x == 0) {
;     unsigned* bar = b.bar;
;     __builtin_amdgcn_s_waitcnt(0);
;     unsigned nloc = b.st[0], nx = b.st[1];
;     if (nloc == 0u) { xcd_barrier_complete(bar, b.x, nloc, nx); b.st[0] = nloc; b.st[1] = nx; }
;     const unsigned old = xb_add(&bar[XB_XSUB(b.x)], 1u);
;     const unsigned gen = old / nloc;
;     if (old + 1u == (gen + 1u) * nloc) {
;       __builtin_amdgcn_fence(__ATOMIC_RELEASE, "agent");
;       asm volatile("s_waitcnt vmcnt(0)" ::: "memory");
;       const unsigned og = xb_add(&bar[XB_TOP], 1u);
;       const unsigned tg = og / nx;
;       if (og + 1u == (tg + 1u) * nx) xb_add(&bar[XB_TOPGEN], 1u);
;       else XB_SPIN(xb_ld(&bar[XB_TOPGEN]) == tg, bar);
;       __builtin_amdgcn_fence(__ATOMIC_ACQUIRE, "agent");
;       xb_add(&bar[XB_XGEN(b.x)], 1u);
;       asm volatile("s_waitcnt vmcnt(0)" ::: "memory");
;     } else {
;       XB_SPIN(xb_ld(&bar[XB_XGEN(b.x)]) == gen, bar);
;       __builtin_amdgcn_fence(__ATOMIC_ACQUIRE, "agent");
;       asm volatile("s_waitcnt vmcnt(0)" ::: "memory");
;     }
;   }
;   __syncthreads();
; }
.LBB0_404:
	s_waitcnt vmcnt(0)
	s_waitcnt lgkmcnt(0)
	s_barrier
	s_mov_b64 s[0:1], exec
	v_readlane_b32 s4, v251, 1
	v_readlane_b32 s5, v251, 2
	s_and_b64 s[4:5], s[0:1], s[4:5]
	s_mov_b64 exec, s[4:5]
	s_cbranch_execz .LBB0_452
	s_waitcnt vmcnt(0) expcnt(0) lgkmcnt(0)
	ds_read_b32 v2, v193
	ds_read_b32 v0, v194
	global_atomic_add v3, v[176:177], v195, off sc0
	v_readlane_b32 s14, v251, 3
	v_readlane_b32 s15, v251, 4
	s_waitcnt lgkmcnt(0)
	v_cvt_f32_u32_e32 v1, v2
	v_sub_u32_e32 v4, 0, v2
	v_rcp_iflag_f32_e32 v1, v1
	s_add_u32 s14, s14, 0x2480
	s_addc_u32 s15, s15, 0
	v_mul_f32_e32 v1, 0x4f7ffffe, v1
	v_cvt_u32_f32_e32 v1, v1
	v_mul_lo_u32 v4, v4, v1
	v_mul_hi_u32 v4, v1, v4
	v_add_u32_e32 v1, v1, v4
	s_waitcnt vmcnt(0)
	v_mul_hi_u32 v1, v3, v1
	v_mul_lo_u32 v4, v1, v2
	v_sub_u32_e32 v4, v3, v4
	v_add_u32_e32 v5, 1, v1
	v_cmp_ge_u32_e32 vcc, v4, v2
	v_add_u32_e32 v3, 1, v3
	s_nop 1
	v_cndmask_b32_e32 v1, v1, v5, vcc
	v_sub_u32_e32 v5, v4, v2
	v_cndmask_b32_e32 v4, v4, v5, vcc
	v_add_u32_e32 v5, 1, v1
	v_cmp_ge_u32_e32 vcc, v4, v2
	s_nop 1
	v_cndmask_b32_e32 v1, v1, v5, vcc
	v_mul_lo_u32 v4, v2, v1
	v_add_u32_e32 v2, v4, v2
	v_mul_lo_u32 v5, v1, v0
	v_cmp_eq_u32_e32 vcc, v3, v2
	s_and_saveexec_b64 s[4:5], vcc
	s_cbranch_execz Lxb4_poll
	buffer_wbl2 sc1
	s_waitcnt vmcnt(0)
	global_atomic_add v181, v195, s[14:15]
	global_atomic_add v181, v195, s[14:15] offset:256
	global_atomic_add v181, v195, s[14:15] offset:512
	global_atomic_add v181, v195, s[14:15] offset:768
	global_atomic_add v181, v195, s[14:15] offset:1024
	global_atomic_add v181, v195, s[14:15] offset:1280
	global_atomic_add v181, v195, s[14:15] offset:1536
	global_atomic_add v181, v195, s[14:15] offset:1792
	global_atomic_add v181, v195, s[14:15] offset:2048
	global_atomic_add v181, v195, s[14:15] offset:2304
	global_atomic_add v181, v195, s[14:15] offset:2560
	global_atomic_add v181, v195, s[14:15] offset:2816
	global_atomic_add v181, v195, s[14:15] offset:3072
	global_atomic_add v181, v195, s[14:15] offset:3328
	global_atomic_add v181, v195, s[14:15] offset:3584
	global_atomic_add v181, v195, s[14:15] offset:3840
Lxb4_poll:
	s_or_b64 exec, exec, s[4:5]
	v_subrev_u32_e32 v4, s14, v176
	v_add_u32_e32 v4, 0x1080, v4
	s_mov_b32 s6, 0

; DEV unsigned xb_ld(unsigned* p) { return __hip_atomic_load(p, __ATOMIC_RELAXED, __HIP_MEMORY_SCOPE_AGENT); }
; DEV unsigned xb_add(unsigned* p, unsigned v) { return __hip_atomic_fetch_add(p, v, __ATOMIC_RELAXED, __HIP_MEMORY_SCOPE_AGENT); }
; #define XB_SPIN(cond, bar) do { unsigned _sp = 0; while (cond) { __builtin_amdgcn_s_sleep(1); \
;     if ((++_sp & 255u) == 0u) { if (xb_ld(&(bar)[XB_TMO])) break; if (_sp > XB_SPIN_CAP) { atomicAdd(&(bar)[XB_TMO], 1u); break; } } } } while (0)
; DEV void xcd_barrier(const XcdBarrier& b) {
;   asm volatile("s_waitcnt vmcnt(0)" ::: "memory");
;   __syncthreads();
;   if (threadIdx.x == 0) {
;     unsigned* bar = b.bar;
;     __builtin_amdgcn_s_waitcnt(0);
;     unsigned nloc = b.st[0], nx = b.st[1];
;     if (nloc == 0u) { xcd_barrier_complete(bar, b.x, nloc, nx); b.st[0] = nloc; b.st[1] = nx; }
;     const unsigned old = xb_add(&bar[XB_XSUB(b.x)], 1u);
;     const unsigned gen = old / nloc;
;     if (old + 1u == (gen + 1u) * nloc) {
;       __builtin_amdgcn_fence(__ATOMIC_RELEASE, "agent");
;       asm volatile("s_waitcnt vmcnt(0)" ::: "memory");
;       const unsigned og = xb_add(&bar[XB_TOP], 1u);
;       const unsigned tg = og / nx;
;       if (og + 1u == (tg + 1u) * nx) xb_add(&bar[XB_TOPGEN], 1u);
;       else XB_SPIN(xb_ld(&bar[XB_TOPGEN]) == tg, bar);
;       __builtin_amdgcn_fence(__ATOMIC_ACQUIRE, "agent");
;       xb_add(&bar[XB_XGEN(b.x)], 1u);
;       asm volatile("s_waitcnt vmcnt(0)" ::: "memory");
;     } else {
;       XB_SPIN(xb_ld(&bar[XB_XGEN(b.x)]) == gen, bar);
;       __builtin_amdgcn_fence(__ATOMIC_ACQUIRE, "agent");
;       asm volatile("s_waitcnt vmcnt(0)" ::: "memory");
;     }
;   }
;   __syncthreads();
; }
.LBB0_461:
	s_waitcnt vmcnt(0)
	s_waitcnt lgkmcnt(0)
	s_barrier
	s_mov_b64 s[0:1], exec
	v_readlane_b32 s4, v251, 1
	v_readlane_b32 s5, v251, 2
	s_and_b64 s[4:5], s[0:1], s[4:5]
	s_mov_b64 exec, s[4:5]
	s_cbranch_execz .LBB0_509
	s_waitcnt vmcnt(0) expcnt(0) lgkmcnt(0)
	ds_read_b32 v2, v193
	ds_read_b32 v0, v194
	global_atomic_add v3, v[176:177], v195, off sc0
	v_readlane_b32 s14, v251, 3
	v_readlane_b32 s15, v251, 4
	s_waitcnt lgkmcnt(0)
	v_cvt_f32_u32_e32 v1, v2
	v_sub_u32_e32 v4, 0, v2
	v_rcp_iflag_f32_e32 v1, v1
	s_add_u32 s14, s14, 0x2480
	s_addc_u32 s15, s15, 0
	v_mul_f32_e32 v1, 0x4f7ffffe, v1
	v_cvt_u32_f32_e32 v1, v1
	v_mul_lo_u32 v4, v4, v1
	v_mul_hi_u32 v4, v1, v4
	v_add_u32_e32 v1, v1, v4
	s_waitcnt vmcnt(0)
	v_mul_hi_u32 v1, v3, v1
	v_mul_lo_u32 v4, v1, v2
	v_sub_u32_e32 v4, v3, v4
	v_add_u32_e32 v5, 1, v1
	v_cmp_ge_u32_e32 vcc, v4, v2
	v_add_u32_e32 v3, 1, v3
	s_nop 1
	v_cndmask_b32_e32 v1, v1, v5, vcc
	v_sub_u32_e32 v5, v4, v2
	v_cndmask_b32_e32 v4, v4, v5, vcc
	v_add_u32_e32 v5, 1, v1
	v_cmp_ge_u32_e32 vcc, v4, v2
	s_nop 1
	v_cndmask_b32_e32 v1, v1, v5, vcc
	v_mul_lo_u32 v4, v2, v1
	v_add_u32_e32 v2, v4, v2
	v_mul_lo_u32 v5, v1, v0
	v_cmp_eq_u32_e32 vcc, v3, v2
	s_and_saveexec_b64 s[4:5], vcc
	s_cbranch_execz Lxb5_poll
	buffer_wbl2 sc1
	s_waitcnt vmcnt(0)
	global_atomic_add v181, v195, s[14:15]
	global_atomic_add v181, v195, s[14:15] offset:256
	global_atomic_add v181, v195, s[14:15] offset:512
	global_atomic_add v181, v195, s[14:15] offset:768
	global_atomic_add v181, v195, s[14:15] offset:1024
	global_atomic_add v181, v195, s[14:15] offset:1280
	global_atomic_add v181, v195, s[14:15] offset:1536
	global_atomic_add v181, v195, s[14:15] offset:1792
	global_atomic_add v181, v195, s[14:15] offset:2048
	global_atomic_add v181, v195, s[14:15] offset:2304
	global_atomic_add v181, v195, s[14:15] offset:2560
	global_atomic_add v181, v195, s[14:15] offset:2816
	global_atomic_add v181, v195, s[14:15] offset:3072
	global_atomic_add v181, v195, s[14:15] offset:3328
	global_atomic_add v181, v195, s[14:15] offset:3584
	global_atomic_add v181, v195, s[14:15] offset:3840
Lxb5_poll:
	s_or_b64 exec, exec, s[4:5]
	v_subrev_u32_e32 v4, s14, v176
	v_add_u32_e32 v4, 0x1080, v4
	s_mov_b32 s6, 0

; DEV unsigned xb_ld(unsigned* p) { return __hip_atomic_load(p, __ATOMIC_RELAXED, __HIP_MEMORY_SCOPE_AGENT); }
; DEV unsigned xb_add(unsigned* p, unsigned v) { return __hip_atomic_fetch_add(p, v, __ATOMIC_RELAXED, __HIP_MEMORY_SCOPE_AGENT); }
; #define XB_SPIN(cond, bar) do { unsigned _sp = 0; while (cond) { __builtin_amdgcn_s_sleep(1); \
;     if ((++_sp & 255u) == 0u) { if (xb_ld(&(bar)[XB_TMO])) break; if (_sp > XB_SPIN_CAP) { atomicAdd(&(bar)[XB_TMO], 1u); break; } } } } while (0)
; DEV void xcd_barrier(const XcdBarrier& b) {
;   asm volatile("s_waitcnt vmcnt(0)" ::: "memory");
;   __syncthreads();
;   if (threadIdx.x == 0) {
;     unsigned* bar = b.bar;
;     __builtin_amdgcn_s_waitcnt(0);
;     unsigned nloc = b.st[0], nx = b.st[1];
;     if (nloc == 0u) { xcd_barrier_complete(bar, b.x, nloc, nx); b.st[0] = nloc; b.st[1] = nx; }
;     const unsigned old = xb_add(&bar[XB_XSUB(b.x)], 1u);
;     const unsigned gen = old / nloc;
;     if (old + 1u == (gen + 1u) * nloc) {
;       __builtin_amdgcn_fence(__ATOMIC_RELEASE, "agent");
;       asm volatile("s_waitcnt vmcnt(0)" ::: "memory");
;       const unsigned og = xb_add(&bar[XB_TOP], 1u);
;       const unsigned tg = og / nx;
;       if (og + 1u == (tg + 1u) * nx) xb_add(&bar[XB_TOPGEN], 1u);
;       else XB_SPIN(xb_ld(&bar[XB_TOPGEN]) == tg, bar);
;       __builtin_amdgcn_fence(__ATOMIC_ACQUIRE, "agent");
;       xb_add(&bar[XB_XGEN(b.x)], 1u);
;       asm volatile("s_waitcnt vmcnt(0)" ::: "memory");
;     } else {
;       XB_SPIN(xb_ld(&bar[XB_XGEN(b.x)]) == gen, bar);
;       __builtin_amdgcn_fence(__ATOMIC_ACQUIRE, "agent");
;       asm volatile("s_waitcnt vmcnt(0)" ::: "memory");
;     }
;   }
;   __syncthreads();
; }
.LBB0_514:
	s_or_b64 exec, exec, s[0:1]
	s_waitcnt vmcnt(0)
	s_waitcnt lgkmcnt(0)
	s_barrier
	s_mov_b64 s[0:1], exec
	v_readlane_b32 s4, v251, 1
	v_readlane_b32 s5, v251, 2
	s_and_b64 s[4:5], s[0:1], s[4:5]
	s_mov_b64 exec, s[4:5]
	s_cbranch_execz .LBB0_562
	s_waitcnt vmcnt(0) expcnt(0) lgkmcnt(0)
	ds_read_b32 v2, v193
	ds_read_b32 v0, v194
	global_atomic_add v3, v[176:177], v195, off sc0
	v_readlane_b32 s14, v251, 3
	v_readlane_b32 s15, v251, 4
	s_waitcnt lgkmcnt(0)
	v_cvt_f32_u32_e32 v1, v2
	v_sub_u32_e32 v4, 0, v2
	v_rcp_iflag_f32_e32 v1, v1
	s_add_u32 s14, s14, 0x2480
	s_addc_u32 s15, s15, 0
	v_mul_f32_e32 v1, 0x4f7ffffe, v1
	v_cvt_u32_f32_e32 v1, v1
	v_mul_lo_u32 v4, v4, v1
	v_mul_hi_u32 v4, v1, v4
	v_add_u32_e32 v1, v1, v4
	s_waitcnt vmcnt(0)
	v_mul_hi_u32 v1, v3, v1
	v_mul_lo_u32 v4, v1, v2
	v_sub_u32_e32 v4, v3, v4
	v_add_u32_e32 v5, 1, v1
	v_cmp_ge_u32_e32 vcc, v4, v2
	v_add_u32_e32 v3, 1, v3
	s_nop 1
	v_cndmask_b32_e32 v1, v1, v5, vcc
	v_sub_u32_e32 v5, v4, v2
	v_cndmask_b32_e32 v4, v4, v5, vcc
	v_add_u32_e32 v5, 1, v1
	v_cmp_ge_u32_e32 vcc, v4, v2
	s_nop 1
	v_cndmask_b32_e32 v1, v1, v5, vcc
	v_mul_lo_u32 v4, v2, v1
	v_add_u32_e32 v2, v4, v2
	v_mul_lo_u32 v5, v1, v0
	v_cmp_eq_u32_e32 vcc, v3, v2
	s_and_saveexec_b64 s[4:5], vcc
	s_cbranch_execz Lxb6_poll
	buffer_wbl2 sc1
	s_waitcnt vmcnt(0)
	global_atomic_add v181, v195, s[14:15]
	global_atomic_add v181, v195, s[14:15] offset:256
	global_atomic_add v181, v195, s[14:15] offset:512
	global_atomic_add v181, v195, s[14:15] offset:768
	global_atomic_add v181, v195, s[14:15] offset:1024
	global_atomic_add v181, v195, s[14:15] offset:1280
	global_atomic_add v181, v195, s[14:15] offset:1536
	global_atomic_add v181, v195, s[14:15] offset:1792
	global_atomic_add v181, v195, s[14:15] offset:2048
	global_atomic_add v181, v195, s[14:15] offset:2304
	global_atomic_add v181, v195, s[14:15] offset:2560
	global_atomic_add v181, v195, s[14:15] offset:2816
	global_atomic_add v181, v195, s[14:15] offset:3072
	global_atomic_add v181, v195, s[14:15] offset:3328
	global_atomic_add v181, v195, s[14:15] offset:3584
	global_atomic_add v181, v195, s[14:15] offset:3840
Lxb6_poll:
	s_or_b64 exec, exec, s[4:5]
	v_subrev_u32_e32 v4, s14, v176
	v_add_u32_e32 v4, 0x1080, v4
	s_mov_b32 s6, 0

; DEV unsigned xb_ld(unsigned* p) { return __hip_atomic_load(p, __ATOMIC_RELAXED, __HIP_MEMORY_SCOPE_AGENT); }
; DEV unsigned xb_add(unsigned* p, unsigned v) { return __hip_atomic_fetch_add(p, v, __ATOMIC_RELAXED, __HIP_MEMORY_SCOPE_AGENT); }
; #define XB_SPIN(cond, bar) do { unsigned _sp = 0; while (cond) { __builtin_amdgcn_s_sleep(1); \
;     if ((++_sp & 255u) == 0u) { if (xb_ld(&(bar)[XB_TMO])) break; if (_sp > XB_SPIN_CAP) { atomicAdd(&(bar)[XB_TMO], 1u); break; } } } } while (0)
; DEV void xcd_barrier(const XcdBarrier& b) {
;   asm volatile("s_waitcnt vmcnt(0)" ::: "memory");
;   __syncthreads();
;   if (threadIdx.x == 0) {
;     unsigned* bar = b.bar;
;     __builtin_amdgcn_s_waitcnt(0);
;     unsigned nloc = b.st[0], nx = b.st[1];
;     if (nloc == 0u) { xcd_barrier_complete(bar, b.x, nloc, nx); b.st[0] = nloc; b.st[1] = nx; }
;     const unsigned old = xb_add(&bar[XB_XSUB(b.x)], 1u);
;     const unsigned gen = old / nloc;
;     if (old + 1u == (gen + 1u) * nloc) {
;       __builtin_amdgcn_fence(__ATOMIC_RELEASE, "agent");
;       asm volatile("s_waitcnt vmcnt(0)" ::: "memory");
;       const unsigned og = xb_add(&bar[XB_TOP], 1u);
;       const unsigned tg = og / nx;
;       if (og + 1u == (tg + 1u) * nx) xb_add(&bar[XB_TOPGEN], 1u);
;       else XB_SPIN(xb_ld(&bar[XB_TOPGEN]) == tg, bar);
;       __builtin_amdgcn_fence(__ATOMIC_ACQUIRE, "agent");
;       xb_add(&bar[XB_XGEN(b.x)], 1u);
;       asm volatile("s_waitcnt vmcnt(0)" ::: "memory");
;     } else {
;       XB_SPIN(xb_ld(&bar[XB_XGEN(b.x)]) == gen, bar);
;       __builtin_amdgcn_fence(__ATOMIC_ACQUIRE, "agent");
;       asm volatile("s_waitcnt vmcnt(0)" ::: "memory");
;     }
;   }
;   __syncthreads();
; }
.LBB0_567:
	s_waitcnt vmcnt(0)
	s_waitcnt lgkmcnt(0)
	s_barrier
	s_mov_b64 s[0:1], exec
	v_readlane_b32 s4, v251, 1
	v_readlane_b32 s5, v251, 2
	s_and_b64 s[4:5], s[0:1], s[4:5]
	s_mov_b64 exec, s[4:5]
	s_cbranch_execz .LBB0_615
	s_waitcnt vmcnt(0) expcnt(0) lgkmcnt(0)
	ds_read_b32 v2, v193
	ds_read_b32 v0, v194
	global_atomic_add v3, v[176:177], v195, off sc0
	v_readlane_b32 s14, v251, 3
	v_readlane_b32 s15, v251, 4
	s_waitcnt lgkmcnt(0)
	v_cvt_f32_u32_e32 v1, v2
	v_sub_u32_e32 v4, 0, v2
	v_rcp_iflag_f32_e32 v1, v1
	s_add_u32 s14, s14, 0x2480
	s_addc_u32 s15, s15, 0
	v_mul_f32_e32 v1, 0x4f7ffffe, v1
	v_cvt_u32_f32_e32 v1, v1
	v_mul_lo_u32 v4, v4, v1
	v_mul_hi_u32 v4, v1, v4
	v_add_u32_e32 v1, v1, v4
	s_waitcnt vmcnt(0)
	v_mul_hi_u32 v1, v3, v1
	v_mul_lo_u32 v4, v1, v2
	v_sub_u32_e32 v4, v3, v4
	v_add_u32_e32 v5, 1, v1
	v_cmp_ge_u32_e32 vcc, v4, v2
	v_add_u32_e32 v3, 1, v3
	s_nop 1
	v_cndmask_b32_e32 v1, v1, v5, vcc
	v_sub_u32_e32 v5, v4, v2
	v_cndmask_b32_e32 v4, v4, v5, vcc
	v_add_u32_e32 v5, 1, v1
	v_cmp_ge_u32_e32 vcc, v4, v2
	s_nop 1
	v_cndmask_b32_e32 v1, v1, v5, vcc
	v_mul_lo_u32 v4, v2, v1
	v_add_u32_e32 v2, v4, v2
	v_mul_lo_u32 v5, v1, v0
	v_cmp_eq_u32_e32 vcc, v3, v2
	s_and_saveexec_b64 s[4:5], vcc
	s_cbranch_execz Lxb7_poll
	buffer_wbl2 sc1
	s_waitcnt vmcnt(0)
	global_atomic_add v181, v195, s[14:15]
	global_atomic_add v181, v195, s[14:15] offset:256
	global_atomic_add v181, v195, s[14:15] offset:512
	global_atomic_add v181, v195, s[14:15] offset:768
	global_atomic_add v181, v195, s[14:15] offset:1024
	global_atomic_add v181, v195, s[14:15] offset:1280
	global_atomic_add v181, v195, s[14:15] offset:1536
	global_atomic_add v181, v195, s[14:15] offset:1792
	global_atomic_add v181, v195, s[14:15] offset:2048
	global_atomic_add v181, v195, s[14:15] offset:2304
	global_atomic_add v181, v195, s[14:15] offset:2560
	global_atomic_add v181, v195, s[14:15] offset:2816
	global_atomic_add v181, v195, s[14:15] offset:3072
	global_atomic_add v181, v195, s[14:15] offset:3328
	global_atomic_add v181, v195, s[14:15] offset:3584
	global_atomic_add v181, v195, s[14:15] offset:3840
Lxb7_poll:
	s_or_b64 exec, exec, s[4:5]
	v_subrev_u32_e32 v4, s14, v176
	v_add_u32_e32 v4, 0x1080, v4
	s_mov_b32 s6, 0

; DEV unsigned xb_ld(unsigned* p) { return __hip_atomic_load(p, __ATOMIC_RELAXED, __HIP_MEMORY_SCOPE_AGENT); }
; DEV unsigned xb_add(unsigned* p, unsigned v) { return __hip_atomic_fetch_add(p, v, __ATOMIC_RELAXED, __HIP_MEMORY_SCOPE_AGENT); }
; #define XB_SPIN(cond, bar) do { unsigned _sp = 0; while (cond) { __builtin_amdgcn_s_sleep(1); \
;     if ((++_sp & 255u) == 0u) { if (xb_ld(&(bar)[XB_TMO])) break; if (_sp > XB_SPIN_CAP) { atomicAdd(&(bar)[XB_TMO], 1u); break; } } } } while (0)
; DEV void xcd_barrier(const XcdBarrier& b) {
;   asm volatile("s_waitcnt vmcnt(0)" ::: "memory");
;   __syncthreads();
;   if (threadIdx.x == 0) {
;     unsigned* bar = b.bar;
;     __builtin_amdgcn_s_waitcnt(0);
;     unsigned nloc = b.st[0], nx = b.st[1];
;     if (nloc == 0u) { xcd_barrier_complete(bar, b.x, nloc, nx); b.st[0] = nloc; b.st[1] = nx; }
;     const unsigned old = xb_add(&bar[XB_XSUB(b.x)], 1u);
;     const unsigned gen = old / nloc;
;     if (old + 1u == (gen + 1u) * nloc) {
;       __builtin_amdgcn_fence(__ATOMIC_RELEASE, "agent");
;       asm volatile("s_waitcnt vmcnt(0)" ::: "memory");
;       const unsigned og = xb_add(&bar[XB_TOP], 1u);
;       const unsigned tg = og / nx;
;       if (og + 1u == (tg + 1u) * nx) xb_add(&bar[XB_TOPGEN], 1u);
;       else XB_SPIN(xb_ld(&bar[XB_TOPGEN]) == tg, bar);
;       __builtin_amdgcn_fence(__ATOMIC_ACQUIRE, "agent");
;       xb_add(&bar[XB_XGEN(b.x)], 1u);
;       asm volatile("s_waitcnt vmcnt(0)" ::: "memory");
;     } else {
;       XB_SPIN(xb_ld(&bar[XB_XGEN(b.x)]) == gen, bar);
;       __builtin_amdgcn_fence(__ATOMIC_ACQUIRE, "agent");
;       asm volatile("s_waitcnt vmcnt(0)" ::: "memory");
;     }
;   }
;   __syncthreads();
; }
.LBB0_637:
	s_waitcnt vmcnt(0)
	s_waitcnt lgkmcnt(0)
	s_barrier
	s_mov_b64 s[0:1], exec
	v_readlane_b32 s4, v251, 1
	v_readlane_b32 s5, v251, 2
	s_and_b64 s[4:5], s[0:1], s[4:5]
	s_mov_b64 exec, s[4:5]
	s_cbranch_execz .LBB0_685
	s_waitcnt vmcnt(0) expcnt(0) lgkmcnt(0)
	ds_read_b32 v2, v193
	ds_read_b32 v0, v194
	global_atomic_add v3, v[176:177], v195, off sc0
	v_readlane_b32 s14, v251, 3
	v_readlane_b32 s15, v251, 4
	s_waitcnt lgkmcnt(0)
	v_cvt_f32_u32_e32 v1, v2
	v_sub_u32_e32 v4, 0, v2
	v_rcp_iflag_f32_e32 v1, v1
	s_add_u32 s14, s14, 0x2480
	s_addc_u32 s15, s15, 0
	v_mul_f32_e32 v1, 0x4f7ffffe, v1
	v_cvt_u32_f32_e32 v1, v1
	v_mul_lo_u32 v4, v4, v1
	v_mul_hi_u32 v4, v1, v4
	v_add_u32_e32 v1, v1, v4
	s_waitcnt vmcnt(0)
	v_mul_hi_u32 v1, v3, v1
	v_mul_lo_u32 v4, v1, v2
	v_sub_u32_e32 v4, v3, v4
	v_add_u32_e32 v5, 1, v1
	v_cmp_ge_u32_e32 vcc, v4, v2
	v_add_u32_e32 v3, 1, v3
	s_nop 1
	v_cndmask_b32_e32 v1, v1, v5, vcc
	v_sub_u32_e32 v5, v4, v2
	v_cndmask_b32_e32 v4, v4, v5, vcc
	v_add_u32_e32 v5, 1, v1
	v_cmp_ge_u32_e32 vcc, v4, v2
	s_nop 1
	v_cndmask_b32_e32 v1, v1, v5, vcc
	v_mul_lo_u32 v4, v2, v1
	v_add_u32_e32 v2, v4, v2
	v_mul_lo_u32 v5, v1, v0
	v_cmp_eq_u32_e32 vcc, v3, v2
	s_and_saveexec_b64 s[4:5], vcc
	s_cbranch_execz Lxb8_poll
	buffer_wbl2 sc1
	s_waitcnt vmcnt(0)
	global_atomic_add v181, v195, s[14:15]
	global_atomic_add v181, v195, s[14:15] offset:256
	global_atomic_add v181, v195, s[14:15] offset:512
	global_atomic_add v181, v195, s[14:15] offset:768
	global_atomic_add v181, v195, s[14:15] offset:1024
	global_atomic_add v181, v195, s[14:15] offset:1280
	global_atomic_add v181, v195, s[14:15] offset:1536
	global_atomic_add v181, v195, s[14:15] offset:1792
	global_atomic_add v181, v195, s[14:15] offset:2048
	global_atomic_add v181, v195, s[14:15] offset:2304
	global_atomic_add v181, v195, s[14:15] offset:2560
	global_atomic_add v181, v195, s[14:15] offset:2816
	global_atomic_add v181, v195, s[14:15] offset:3072
	global_atomic_add v181, v195, s[14:15] offset:3328
	global_atomic_add v181, v195, s[14:15] offset:3584
	global_atomic_add v181, v195, s[14:15] offset:3840
Lxb8_poll:
	s_or_b64 exec, exec, s[4:5]
	v_subrev_u32_e32 v4, s14, v176
	v_add_u32_e32 v4, 0x1080, v4
	s_mov_b32 s6, 0

; DEV unsigned xb_ld(unsigned* p) { return __hip_atomic_load(p, __ATOMIC_RELAXED, __HIP_MEMORY_SCOPE_AGENT); }
; DEV unsigned xb_add(unsigned* p, unsigned v) { return __hip_atomic_fetch_add(p, v, __ATOMIC_RELAXED, __HIP_MEMORY_SCOPE_AGENT); }
; #define XB_SPIN(cond, bar) do { unsigned _sp = 0; while (cond) { __builtin_amdgcn_s_sleep(1); \
;     if ((++_sp & 255u) == 0u) { if (xb_ld(&(bar)[XB_TMO])) break; if (_sp > XB_SPIN_CAP) { atomicAdd(&(bar)[XB_TMO], 1u); break; } } } } while (0)
; DEV void xcd_barrier(const XcdBarrier& b) {
;   asm volatile("s_waitcnt vmcnt(0)" ::: "memory");
;   __syncthreads();
;   if (threadIdx.x == 0) {
;     unsigned* bar = b.bar;
;     __builtin_amdgcn_s_waitcnt(0);
;     unsigned nloc = b.st[0], nx = b.st[1];
;     if (nloc == 0u) { xcd_barrier_complete(bar, b.x, nloc, nx); b.st[0] = nloc; b.st[1] = nx; }
;     const unsigned old = xb_add(&bar[XB_XSUB(b.x)], 1u);
;     const unsigned gen = old / nloc;
;     if (old + 1u == (gen + 1u) * nloc) {
;       __builtin_amdgcn_fence(__ATOMIC_RELEASE, "agent");
;       asm volatile("s_waitcnt vmcnt(0)" ::: "memory");
;       const unsigned og = xb_add(&bar[XB_TOP], 1u);
;       const unsigned tg = og / nx;
;       if (og + 1u == (tg + 1u) * nx) xb_add(&bar[XB_TOPGEN], 1u);
;       else XB_SPIN(xb_ld(&bar[XB_TOPGEN]) == tg, bar);
;       __builtin_amdgcn_fence(__ATOMIC_ACQUIRE, "agent");
;       xb_add(&bar[XB_XGEN(b.x)], 1u);
;       asm volatile("s_waitcnt vmcnt(0)" ::: "memory");
;     } else {
;       XB_SPIN(xb_ld(&bar[XB_XGEN(b.x)]) == gen, bar);
;       __builtin_amdgcn_fence(__ATOMIC_ACQUIRE, "agent");
;       asm volatile("s_waitcnt vmcnt(0)" ::: "memory");
;     }
;   }
;   __syncthreads();
; }
.LBB0_778:
	s_waitcnt vmcnt(0) expcnt(0) lgkmcnt(0)
	ds_read_b32 v2, v193
	ds_read_b32 v0, v194
	global_atomic_add v3, v[176:177], v195, off sc0
	v_readlane_b32 s16, v251, 3
	v_readlane_b32 s17, v251, 4
	s_waitcnt lgkmcnt(0)
	v_cvt_f32_u32_e32 v1, v2
	v_sub_u32_e32 v4, 0, v2
	v_rcp_iflag_f32_e32 v1, v1
	s_add_u32 s16, s16, 0x2480
	s_addc_u32 s17, s17, 0
	v_mul_f32_e32 v1, 0x4f7ffffe, v1
	v_cvt_u32_f32_e32 v1, v1
	v_mul_lo_u32 v4, v4, v1
	v_mul_hi_u32 v4, v1, v4
	v_add_u32_e32 v1, v1, v4
	s_waitcnt vmcnt(0)
	v_mul_hi_u32 v1, v3, v1
	v_mul_lo_u32 v4, v1, v2
	v_sub_u32_e32 v4, v3, v4
	v_add_u32_e32 v5, 1, v1
	v_cmp_ge_u32_e32 vcc, v4, v2
	v_add_u32_e32 v3, 1, v3
	s_nop 1
	v_cndmask_b32_e32 v1, v1, v5, vcc
	v_sub_u32_e32 v5, v4, v2
	v_cndmask_b32_e32 v4, v4, v5, vcc
	v_add_u32_e32 v5, 1, v1
	v_cmp_ge_u32_e32 vcc, v4, v2
	s_nop 1
	v_cndmask_b32_e32 v1, v1, v5, vcc
	v_mul_lo_u32 v4, v2, v1
	v_add_u32_e32 v2, v4, v2
	v_mul_lo_u32 v5, v1, v0
	v_cmp_eq_u32_e32 vcc, v3, v2
	s_and_saveexec_b64 s[14:15], vcc
	s_cbranch_execz Lxb9_poll
	buffer_wbl2 sc1
	s_waitcnt vmcnt(0)
	global_atomic_add v181, v195, s[16:17]
	global_atomic_add v181, v195, s[16:17] offset:256
	global_atomic_add v181, v195, s[16:17] offset:512
	global_atomic_add v181, v195, s[16:17] offset:768
	global_atomic_add v181, v195, s[16:17] offset:1024
	global_atomic_add v181, v195, s[16:17] offset:1280
	global_atomic_add v181, v195, s[16:17] offset:1536
	global_atomic_add v181, v195, s[16:17] offset:1792
	global_atomic_add v181, v195, s[16:17] offset:2048
	global_atomic_add v181, v195, s[16:17] offset:2304
	global_atomic_add v181, v195, s[16:17] offset:2560
	global_atomic_add v181, v195, s[16:17] offset:2816
	global_atomic_add v181, v195, s[16:17] offset:3072
	global_atomic_add v181, v195, s[16:17] offset:3328
	global_atomic_add v181, v195, s[16:17] offset:3584
	global_atomic_add v181, v195, s[16:17] offset:3840
Lxb9_poll:
	s_or_b64 exec, exec, s[14:15]
	v_subrev_u32_e32 v4, s16, v176
	v_add_u32_e32 v4, 0x1080, v4
	s_mov_b32 s6, 0
